# whole instruction stream shifted by 4 bytes except the attnA loop (kept at its placement): code-placement trial
# baseline (speedup 1.0000x reference)
; DI unsigned xb_add(unsigned* p, unsigned v) { return __hip_atomic_fetch_add(p, v, __ATOMIC_RELAXED, __HIP_MEMORY_SCOPE_AGENT); }
; DI unsigned xb_xcc_id() { return (unsigned)__builtin_amdgcn_s_getreg((3 << 11) | 20) & 0xFu; }
; #define LAS __attribute__((address_space(3)))
; DI XcdBarrier xcd_barrier_post(unsigned* bar, volatile LAS unsigned* st) {
;   XcdBarrier b; b.bar = bar; b.st = st;
;   if (threadIdx.x == 0) { const unsigned x = xb_xcc_id(); st[2] = x; (void)xb_add(&bar[XB_XCNT(x)], 1u); }
;   return b;
; }
; __global__ void __launch_bounds__(256, 2) mk_fwd(Params p_in) {
;   __shared__ __attribute__((aligned(16))) unsigned char smem[SMEM_BYTES];
;   const int bid = blockIdx.x, nb = gridDim.x;
;   const int lo = p_in.ph_lo, hi = p_in.ph_hi;
;   Params p = p_in;
;   p.wave = __builtin_amdgcn_readfirstlane((int)(threadIdx.x >> 6));
;     ...
;   __shared__ unsigned xb_words[4];
;   __shared__ int q_slot;
;   XcdBarrier xbar = xcd_barrier_post((unsigned*)(p.ws + WS_CTL), (volatile LAS unsigned*)&xb_words);
_Z6mk_fwd6Params:
	s_nop 0
	s_load_dwordx4 s[56:59], s[0:1], 0x90
	s_load_dword s54, s[0:1], 0xa8
	s_mov_b32 s70, s2
	s_add_u32 s2, s0, 0xa8
	v_and_b32_e32 v1, 0x3ff, v0
	s_addc_u32 s3, s1, 0
	v_readfirstlane_b32 s4, v1
	v_cmp_eq_u32_e64 s[60:61], 0, v1
	s_nop 0
	v_writelane_b32 v253, s4, 0
	s_waitcnt lgkmcnt(0)
	s_add_u32 s4, s56, 0xfc86000
	s_addc_u32 s5, s57, 0
	v_writelane_b32 v253, s4, 1
	s_nop 1
	v_writelane_b32 v253, s5, 2
	s_and_saveexec_b64 s[4:5], s[60:61]
	s_cbranch_execz .LBB0_3
	s_getreg_b32 s8, hwreg(HW_REG_XCC_ID, 0, 4)
	s_and_b32 s8, s8, 15
	s_mov_b64 s[6:7], exec
	v_mov_b32_e32 v2, 0x12008
	v_mov_b32_e32 v3, s8
	ds_write_b32 v2, v3
	v_mbcnt_lo_u32_b32 v2, s6, 0
	v_mbcnt_hi_u32_b32 v2, s7, v2
	v_cmp_eq_u32_e32 vcc, 0, v2
	s_and_b64 s[10:11], exec, vcc
	s_mov_b64 exec, s[10:11]
	s_cbranch_execz .LBB0_3
	s_bcnt1_i32_b64 s6, s[6:7]
	s_lshl_b32 s8, s8, 8
	v_mov_b32_e32 v3, s6
	v_readlane_b32 s6, v253, 1
	v_mov_b32_e32 v2, s8
	v_readlane_b32 s7, v253, 2
	s_nop 4
	global_atomic_add v2, v3, s[6:7] offset:1024
